# attn M phases: one counted lgkmcnt wait per MFMA pair (14 fewer s_waitcnt per loop iteration)
# baseline (speedup 1.0000x reference)
; #define LAS __attribute__((address_space(3)))
; __device__ __forceinline__ void qkt(f32x16& p0, f32x16& p1, const LAS unsigned char* Ks, const bf16x8* qr, const f32x16& negm, int r32, int hi) {
;   bf16x8 kf[12];
; #pragma unroll
;   for (int d0 = 0; d0 < 6; ++d0) { const int cb = (d0 * 16 + hi * 8) * 2;
;     kf[2 * d0] = *(const LAS bf16x8*)(Ks + KSWZ(r32, cb)); kf[2 * d0 + 1] = *(const LAS bf16x8*)(Ks + KSWZ(32 + r32, cb)); }
;   SBAR();
;   p0 = __builtin_amdgcn_mfma_f32_32x32x16_bf16(kf[0], qr[0], negm, 0, 0, 0); p1 = __builtin_amdgcn_mfma_f32_32x32x16_bf16(kf[1], qr[0], negm, 0, 0, 0);
; #pragma unroll
;   for (int d0 = 1; d0 < 6; ++d0) { p0 = __builtin_amdgcn_mfma_f32_32x32x16_bf16(kf[2 * d0], qr[d0], p0, 0, 0, 0); p1 = __builtin_amdgcn_mfma_f32_32x32x16_bf16(kf[2 * d0 + 1], qr[d0], p1, 0, 0, 0); }
; }
; __device__ __forceinline__ int v_st(int k, int c) { const int kk = (k & ~0xC) | ((k & 4) << 1) | ((k & 8) >> 1); return ((kk >> 3) * 4 + (c >> 5)) * 512 + ((kk & 7) * 32 + (c & 31)) * 2; }
; __device__ __forceinline__ int v_rd_base(int lane) { return ((lane & 3) << 3) | (((lane >> 2) & 3) << 6) | (((lane >> 4) & 1) << 5) | (((lane >> 5) & 1) << 8); }
; template <int OFF> __device__ __forceinline__ s16x4 tr_read(int vb) {
;   s16x4 r; asm volatile("ds_read_b64_tr_b16 %0, %1 offset:%2" : "=&v"(r) : "v"(vb), "i"(OFF) : "memory"); return r;
; }
; __device__ __forceinline__ void pv_d0(f32x16* o, int vb, bf16x8 pa0, bf16x8 pa1, bf16x8 pa2, bf16x8 pa3) {
;   const s16x4 a0 = tr_read<v_rd_off(0, 0, 0)>(vb), b0 = tr_read<v_rd_off(0, 0, 1)>(vb), a1 = tr_read<v_rd_off(0, 1, 0)>(vb), b1 = tr_read<v_rd_off(0, 1, 1)>(vb);
;   const s16x4 a2 = tr_read<v_rd_off(0, 2, 0)>(vb), b2 = tr_read<v_rd_off(0, 2, 1)>(vb), a3 = tr_read<v_rd_off(0, 3, 0)>(vb), b3 = tr_read<v_rd_off(0, 3, 1)>(vb);
;   const s16x4 c0 = tr_read<v_rd_off(1, 0, 0)>(vb), d0 = tr_read<v_rd_off(1, 0, 1)>(vb), c1 = tr_read<v_rd_off(1, 1, 0)>(vb), d1 = tr_read<v_rd_off(1, 1, 1)>(vb);
;   const s16x4 c2 = tr_read<v_rd_off(1, 2, 0)>(vb), d2 = tr_read<v_rd_off(1, 2, 1)>(vb), c3 = tr_read<v_rd_off(1, 3, 0)>(vb), d3 = tr_read<v_rd_off(1, 3, 1)>(vb);
;   asm volatile("s_waitcnt lgkmcnt(0)" ::: "memory"); SBAR();
;     ...
;   o[0] = __builtin_amdgcn_mfma_f32_32x32x16_bf16(pa0, PK(a0, b0), o[0], 0, 0, 0); o[1] = __builtin_amdgcn_mfma_f32_32x32x16_bf16(pa0, PK(c0, d0), o[1], 0, 0, 0);
.Lmy_attn_m1:
	ds_read_b64_tr_b16 v[70:71], v174 offset:0x1000
	ds_read_b64_tr_b16 v[72:73], v174 offset:0x1800
	ds_read_b64_tr_b16 v[162:163], v174 offset:0x1200
	ds_read_b64_tr_b16 v[164:165], v174 offset:0x1a00
	ds_read_b64_tr_b16 v[74:75], v174 offset:0x2000
	ds_read_b64_tr_b16 v[76:77], v174 offset:0x2800
	ds_read_b64_tr_b16 v[166:167], v174 offset:0x2200
	ds_read_b64_tr_b16 v[168:169], v174 offset:0x2a00
	ds_read_b64_tr_b16 v[78:79], v174 offset:0x3000
	ds_read_b64_tr_b16 v[80:81], v174 offset:0x3800
	ds_read_b64_tr_b16 v[170:171], v174 offset:0x3200
	ds_read_b64_tr_b16 v[172:173], v174 offset:0x3a00
	s_waitcnt lgkmcnt(12)
	v_mfma_f32_32x32x16_bf16 v[34:49], v[62:65], v[66:69], v[34:49]
	v_mfma_f32_32x32x16_bf16 v[18:33], v[62:65], v[158:161], v[18:33]
	s_waitcnt lgkmcnt(8)
	v_mfma_f32_32x32x16_bf16 v[34:49], v[50:53], v[70:73], v[34:49]
	v_mfma_f32_32x32x16_bf16 v[18:33], v[50:53], v[162:165], v[18:33]
	s_waitcnt lgkmcnt(4)
	v_mfma_f32_32x32x16_bf16 v[34:49], v[54:57], v[74:77], v[34:49]
	v_mfma_f32_32x32x16_bf16 v[18:33], v[54:57], v[166:169], v[18:33]
	v_add_u32_e32 v55, s5, v239
	ds_read_b128 v[50:53], v55 offset:49152
	ds_read_b128 v[158:161], v55 offset:57344
	v_add_u32_e32 v55, s5, v250
	ds_read_b128 v[162:165], v55 offset:49152
	ds_read_b128 v[166:169], v55 offset:57344
	v_add_u32_e32 v55, s5, v251
	s_waitcnt lgkmcnt(4)
	v_mfma_f32_32x32x16_bf16 v[34:49], v[58:61], v[78:81], v[34:49]
	v_mfma_f32_32x32x16_bf16 v[18:33], v[58:61], v[170:173], v[18:33]
	ds_read_b128 v[170:173], v55 offset:49152
	ds_read_b128 v[178:181], v55 offset:57344
	v_add_u32_e32 v55, s5, v252
	ds_read_b128 v[182:185], v55 offset:49152
	ds_read_b128 v[186:189], v55 offset:57344
	v_add_u32_e32 v55, s5, v253
	v_add_u32_e32 v54, s5, v175
	ds_read_b128 v[190:193], v55 offset:49152
	ds_read_b128 v[194:197], v55 offset:57344
	ds_read_b128 v[198:201], v54 offset:49152
	ds_read_b128 v[202:205], v54 offset:57344
	s_waitcnt lgkmcnt(9)
	v_mfma_f32_32x32x16_bf16 v[66:81], v[50:53], v[82:85], v[2:17]
	v_mfma_f32_32x32x16_bf16 v[66:81], v[162:165], v[86:89], v[66:81]
	s_waitcnt lgkmcnt(5)
	v_mfma_f32_32x32x16_bf16 v[66:81], v[170:173], v[90:93], v[66:81]
	v_mfma_f32_32x32x16_bf16 v[66:81], v[182:185], v[94:97], v[66:81]
	s_waitcnt lgkmcnt(1)
	v_mfma_f32_32x32x16_bf16 v[66:81], v[190:193], v[98:101], v[66:81]
	v_mfma_f32_32x32x16_bf16 v[66:81], v[198:201], v[102:105], v[66:81]
	s_waitcnt lgkmcnt(0)
	v_mfma_f32_32x32x16_bf16 v[50:65], v[158:161], v[82:85], v[2:17]
	v_mfma_f32_32x32x16_bf16 v[50:65], v[166:169], v[86:89], v[50:65]
	v_mfma_f32_32x32x16_bf16 v[50:65], v[178:181], v[90:93], v[50:65]
	v_mfma_f32_32x32x16_bf16 v[50:65], v[186:189], v[94:97], v[50:65]
	v_mfma_f32_32x32x16_bf16 v[50:65], v[194:197], v[98:101], v[50:65]
	v_mfma_f32_32x32x16_bf16 v[50:65], v[202:205], v[102:105], v[50:65]
	s_setprio 0
	v_max3_f32 v158, v66, v67, v68
	v_max3_f32 v159, v69, v70, v71
	v_max3_f32 v158, v158, v72, v73
	v_max3_f32 v159, v159, v74, v75
	v_max3_f32 v158, v158, v76, v77
	v_max3_f32 v159, v159, v78, v79
	v_max3_f32 v158, v158, v80, v81
	s_nop 3
	v_max3_f32 v159, v159, v50, v51
	v_max3_f32 v158, v158, v52, v53
	v_max3_f32 v159, v159, v54, v55
	v_max3_f32 v158, v158, v56, v57
	v_max3_f32 v159, v159, v58, v59
	v_max3_f32 v158, v158, v60, v61
	v_max3_f32 v159, v159, v62, v63
	v_max3_f32 v158, v158, v64, v65
	v_max_f32_e32 v159, v158, v159
	v_cmp_ge_f32_e32 vcc, s93, v159
	s_cmp_eq_u64 vcc, exec
	s_barrier
	s_cbranch_scc0 .LBB0_540

; #define LAS __attribute__((address_space(3)))
; __device__ __forceinline__ void qkt(f32x16& p0, f32x16& p1, const LAS unsigned char* Ks, const bf16x8* qr, const f32x16& negm, int r32, int hi) {
;   bf16x8 kf[12];
; #pragma unroll
;   for (int d0 = 0; d0 < 6; ++d0) { const int cb = (d0 * 16 + hi * 8) * 2;
;     kf[2 * d0] = *(const LAS bf16x8*)(Ks + KSWZ(r32, cb)); kf[2 * d0 + 1] = *(const LAS bf16x8*)(Ks + KSWZ(32 + r32, cb)); }
;   SBAR();
;   p0 = __builtin_amdgcn_mfma_f32_32x32x16_bf16(kf[0], qr[0], negm, 0, 0, 0); p1 = __builtin_amdgcn_mfma_f32_32x32x16_bf16(kf[1], qr[0], negm, 0, 0, 0);
; #pragma unroll
;   for (int d0 = 1; d0 < 6; ++d0) { p0 = __builtin_amdgcn_mfma_f32_32x32x16_bf16(kf[2 * d0], qr[d0], p0, 0, 0, 0); p1 = __builtin_amdgcn_mfma_f32_32x32x16_bf16(kf[2 * d0 + 1], qr[d0], p1, 0, 0, 0); }
; }
; __device__ __forceinline__ int v_st(int k, int c) { const int kk = (k & ~0xC) | ((k & 4) << 1) | ((k & 8) >> 1); return ((kk >> 3) * 4 + (c >> 5)) * 512 + ((kk & 7) * 32 + (c & 31)) * 2; }
; __device__ __forceinline__ int v_rd_base(int lane) { return ((lane & 3) << 3) | (((lane >> 2) & 3) << 6) | (((lane >> 4) & 1) << 5) | (((lane >> 5) & 1) << 8); }
; template <int OFF> __device__ __forceinline__ s16x4 tr_read(int vb) {
;   s16x4 r; asm volatile("ds_read_b64_tr_b16 %0, %1 offset:%2" : "=&v"(r) : "v"(vb), "i"(OFF) : "memory"); return r;
; }
; __device__ __forceinline__ void pv_d0(f32x16* o, int vb, bf16x8 pa0, bf16x8 pa1, bf16x8 pa2, bf16x8 pa3) {
;   const s16x4 a0 = tr_read<v_rd_off(0, 0, 0)>(vb), b0 = tr_read<v_rd_off(0, 0, 1)>(vb), a1 = tr_read<v_rd_off(0, 1, 0)>(vb), b1 = tr_read<v_rd_off(0, 1, 1)>(vb);
;   const s16x4 a2 = tr_read<v_rd_off(0, 2, 0)>(vb), b2 = tr_read<v_rd_off(0, 2, 1)>(vb), a3 = tr_read<v_rd_off(0, 3, 0)>(vb), b3 = tr_read<v_rd_off(0, 3, 1)>(vb);
;   const s16x4 c0 = tr_read<v_rd_off(1, 0, 0)>(vb), d0 = tr_read<v_rd_off(1, 0, 1)>(vb), c1 = tr_read<v_rd_off(1, 1, 0)>(vb), d1 = tr_read<v_rd_off(1, 1, 1)>(vb);
;   const s16x4 c2 = tr_read<v_rd_off(1, 2, 0)>(vb), d2 = tr_read<v_rd_off(1, 2, 1)>(vb), c3 = tr_read<v_rd_off(1, 3, 0)>(vb), d3 = tr_read<v_rd_off(1, 3, 1)>(vb);
;   asm volatile("s_waitcnt lgkmcnt(0)" ::: "memory"); SBAR();
;     ...
;   o[0] = __builtin_amdgcn_mfma_f32_32x32x16_bf16(pa0, PK(a0, b0), o[0], 0, 0, 0); o[1] = __builtin_amdgcn_mfma_f32_32x32x16_bf16(pa0, PK(c0, d0), o[1], 0, 0, 0);
.LBB0_531:
	v_pk_add_f32 v[222:223], v[66:67], v[222:223]
	v_pk_add_f32 v[224:225], v[68:69], v[224:225]
	v_pk_add_f32 v[226:227], v[70:71], v[226:227]
	v_pk_add_f32 v[228:229], v[72:73], v[228:229]
	v_pk_add_f32 v[230:231], v[74:75], v[230:231]
	v_pk_add_f32 v[232:233], v[76:77], v[232:233]
	v_pk_add_f32 v[234:235], v[78:79], v[234:235]
	v_pk_add_f32 v[236:237], v[80:81], v[236:237]
	v_pk_add_f32 v[222:223], v[222:223], v[224:225]
	v_pk_add_f32 v[226:227], v[226:227], v[228:229]
	v_pk_add_f32 v[230:231], v[230:231], v[232:233]
	v_pk_add_f32 v[234:235], v[234:235], v[236:237]
	v_pk_add_f32 v[222:223], v[222:223], v[226:227]
	v_pk_add_f32 v[230:231], v[230:231], v[234:235]
	v_pk_add_f32 v[222:223], v[222:223], v[230:231]
	v_add_f32_e32 v222, v222, v223
	v_add_f32_e32 v157, v157, v222
	v_add_u32_e32 v174, s5, v156
	ds_read_b64_tr_b16 v[66:67], v174 offset:0
	ds_read_b64_tr_b16 v[68:69], v174 offset:0x800
	ds_read_b64_tr_b16 v[158:159], v174 offset:0x200
	ds_read_b64_tr_b16 v[160:161], v174 offset:0xa00
	s_waitcnt lgkmcnt(4)
	s_barrier
	s_setprio 2
	ds_read_b64_tr_b16 v[70:71], v174 offset:0x1000
	ds_read_b64_tr_b16 v[72:73], v174 offset:0x1800
	ds_read_b64_tr_b16 v[162:163], v174 offset:0x1200
	ds_read_b64_tr_b16 v[164:165], v174 offset:0x1a00
	ds_read_b64_tr_b16 v[74:75], v174 offset:0x2000
	ds_read_b64_tr_b16 v[76:77], v174 offset:0x2800
	ds_read_b64_tr_b16 v[166:167], v174 offset:0x2200
	ds_read_b64_tr_b16 v[168:169], v174 offset:0x2a00
	ds_read_b64_tr_b16 v[78:79], v174 offset:0x3000
	ds_read_b64_tr_b16 v[80:81], v174 offset:0x3800
	ds_read_b64_tr_b16 v[170:171], v174 offset:0x3200
	ds_read_b64_tr_b16 v[172:173], v174 offset:0x3a00
	s_waitcnt lgkmcnt(12)
	v_mfma_f32_32x32x16_bf16 v[34:49], v[54:57], v[66:69], v[34:49]
	v_mfma_f32_32x32x16_bf16 v[18:33], v[54:57], v[158:161], v[18:33]
	v_add_u32_e32 v55, s10, v239
	s_waitcnt lgkmcnt(8)
	v_mfma_f32_32x32x16_bf16 v[34:49], v[50:53], v[70:73], v[34:49]
	v_mfma_f32_32x32x16_bf16 v[18:33], v[50:53], v[162:165], v[18:33]
	ds_read_b128 v[50:53], v55 offset:49152
	ds_read_b128 v[158:161], v55 offset:57344
	v_add_u32_e32 v55, s10, v250
	s_waitcnt lgkmcnt(6)
	v_mfma_f32_32x32x16_bf16 v[34:49], v[58:61], v[74:77], v[34:49]
	v_mfma_f32_32x32x16_bf16 v[18:33], v[58:61], v[166:169], v[18:33]
	ds_read_b128 v[162:165], v55 offset:49152
	ds_read_b128 v[166:169], v55 offset:57344
	v_add_u32_e32 v55, s10, v251
	s_waitcnt lgkmcnt(4)
	v_mfma_f32_32x32x16_bf16 v[34:49], v[62:65], v[78:81], v[34:49]
	v_mfma_f32_32x32x16_bf16 v[18:33], v[62:65], v[170:173], v[18:33]
	ds_read_b128 v[170:173], v55 offset:49152
	ds_read_b128 v[178:181], v55 offset:57344
	v_add_u32_e32 v55, s10, v252
	ds_read_b128 v[182:185], v55 offset:49152
	ds_read_b128 v[186:189], v55 offset:57344
	v_add_u32_e32 v55, s10, v253
	v_add_u32_e32 v54, s10, v175
	ds_read_b128 v[190:193], v55 offset:49152
	ds_read_b128 v[194:197], v55 offset:57344
	ds_read_b128 v[198:201], v54 offset:49152
	ds_read_b128 v[202:205], v54 offset:57344
	s_waitcnt lgkmcnt(9)
	v_mfma_f32_32x32x16_bf16 v[66:81], v[50:53], v[82:85], v[2:17]
	v_mfma_f32_32x32x16_bf16 v[66:81], v[162:165], v[86:89], v[66:81]
	s_waitcnt lgkmcnt(5)
	v_mfma_f32_32x32x16_bf16 v[66:81], v[170:173], v[90:93], v[66:81]
	v_mfma_f32_32x32x16_bf16 v[66:81], v[182:185], v[94:97], v[66:81]
	s_waitcnt lgkmcnt(1)
	v_mfma_f32_32x32x16_bf16 v[66:81], v[190:193], v[98:101], v[66:81]
	v_mfma_f32_32x32x16_bf16 v[66:81], v[198:201], v[102:105], v[66:81]
	s_waitcnt lgkmcnt(0)
	v_mfma_f32_32x32x16_bf16 v[50:65], v[158:161], v[82:85], v[2:17]
	v_mfma_f32_32x32x16_bf16 v[50:65], v[166:169], v[86:89], v[50:65]
	v_mfma_f32_32x32x16_bf16 v[50:65], v[178:181], v[90:93], v[50:65]
	v_mfma_f32_32x32x16_bf16 v[50:65], v[186:189], v[94:97], v[50:65]
	v_mfma_f32_32x32x16_bf16 v[50:65], v[194:197], v[98:101], v[50:65]
	v_mfma_f32_32x32x16_bf16 v[50:65], v[202:205], v[102:105], v[50:65]
	s_setprio 0
	v_max3_f32 v158, v66, v67, v68
	v_max3_f32 v159, v69, v70, v71
	v_max3_f32 v158, v158, v72, v73
	v_max3_f32 v159, v159, v74, v75
	v_max3_f32 v158, v158, v76, v77
	v_max3_f32 v159, v159, v78, v79
	v_max3_f32 v158, v158, v80, v81
	s_nop 3
	v_max3_f32 v159, v159, v50, v51
	v_max3_f32 v158, v158, v52, v53
	v_max3_f32 v159, v159, v54, v55
	v_max3_f32 v158, v158, v56, v57
	v_max3_f32 v159, v159, v58, v59
	v_max3_f32 v158, v158, v60, v61
	v_max3_f32 v159, v159, v62, v63
	v_max3_f32 v158, v158, v64, v65
	v_max_f32_e32 v159, v158, v159
	v_cmp_ge_f32_e32 vcc, s93, v159
	s_cmp_eq_u64 vcc, exec
	s_barrier
	s_cbranch_scc0 .LBB0_541
